# accumulator zero-init between tiles halved with 64-bit moves in all six GEMM phases (on top of v13)
# speedup vs baseline: 1.0090x; 1.0090x over previous
;     __device__ __forceinline__ const char* a_of(const Unit& u) const { size_t o = A0; if constexpr (NG > 1 || UPT > 1) o = (u.g == 1) ? A1 : o; if constexpr (NG > 2) o = (u.g == 2) ? A2 : o; return (const char*)ws + o; }
;     __device__ __forceinline__ const char* b_of(const Unit& u) const { size_t o = B0; if constexpr (NG > 1 || UPT > 1) o = (u.g == 1) ? B1 : o; if constexpr (NG > 2) o = (u.g == 2) ? B2 : o; return (const char*)ws + o; }
; template <class Epi, class Sched>
; __device__ __forceinline__ void gemm_phase(LAS unsigned char* lds, const int K, const Sched& S, const Epi& E) {
;     ...
;         const bool has_next = S.next(ui + 1, nxt);
;         const char* nA = has_next ? S.a_of(nxt) + (size_t)nxt.pm * tstep : cA; const char* nB = has_next ? S.b_of(nxt) + (size_t)nxt.pn * tstep : cB;
;     ...
; #pragma unroll
;         for (int a = 0; a < 2; ++a)
; #pragma unroll
;             for (int b = 0; b < 2; ++b)
; #pragma unroll
;                 for (int m = 0; m < 4; ++m)
; #pragma unroll
;                     for (int n = 0; n < 2; ++n) acc[a][b][m][n] = (f32x4){0.f, 0.f, 0.f, 0.f};
.LBB0_254:
	s_ashr_i32 s53, s52, 31
	s_lshl_b64 s[54:55], s[52:53], 19
	s_add_u32 s54, s33, s54
	s_addc_u32 s55, s70, s55
	s_and_b64 s[56:57], s[66:67], exec
	s_cselect_b32 s12, s55, s63
	s_cselect_b32 s53, s54, s62
	s_ashr_i32 s51, s50, 31
	s_lshl_b64 s[56:57], s[50:51], 19
	s_add_u32 s56, s10, s56
	s_addc_u32 s57, s11, s57
	s_and_b64 s[66:67], s[66:67], exec
	s_cselect_b32 s51, s57, s65
	s_cselect_b32 s59, s56, s64
	s_add_u32 s62, s62, 0x40080
	s_addc_u32 s63, s63, 0
	s_add_u32 s61, s64, 0x100
	s_addc_u32 s93, s65, 0
	s_mov_b32 s94, -2
	v_mov_b64_e32 v[0:1], 0
	v_mov_b64_e32 v[2:3], 0
	s_waitcnt lgkmcnt(0)
	v_mov_b64_e32 v[4:5], 0
	v_mov_b64_e32 v[6:7], 0
	v_mov_b64_e32 v[16:17], 0
	v_mov_b64_e32 v[18:19], 0
	v_mov_b64_e32 v[20:21], 0
	v_mov_b64_e32 v[22:23], 0
	v_mov_b64_e32 v[32:33], 0
	v_mov_b64_e32 v[34:35], 0
	v_mov_b64_e32 v[36:37], 0
	v_mov_b64_e32 v[38:39], 0
	v_mov_b64_e32 v[48:49], 0
	v_mov_b64_e32 v[50:51], 0
	v_mov_b64_e32 v[52:53], 0
	v_mov_b64_e32 v[54:55], 0
	v_mov_b64_e32 v[8:9], 0
	v_mov_b64_e32 v[10:11], 0
	v_mov_b64_e32 v[12:13], 0
	v_mov_b64_e32 v[14:15], 0
	v_mov_b64_e32 v[24:25], 0
	v_mov_b64_e32 v[26:27], 0
	v_mov_b64_e32 v[28:29], 0
	v_mov_b64_e32 v[30:31], 0
	v_mov_b64_e32 v[40:41], 0
	v_mov_b64_e32 v[42:43], 0
	v_mov_b64_e32 v[44:45], 0
	v_mov_b64_e32 v[46:47], 0
	v_mov_b64_e32 v[56:57], 0
	v_mov_b64_e32 v[58:59], 0
	v_mov_b64_e32 v[60:61], 0
	v_mov_b64_e32 v[62:63], 0
	v_mov_b64_e32 v[64:65], 0
	v_mov_b64_e32 v[66:67], 0
	v_mov_b64_e32 v[68:69], 0
	v_mov_b64_e32 v[70:71], 0
	v_mov_b64_e32 v[80:81], 0
	v_mov_b64_e32 v[82:83], 0
	v_mov_b64_e32 v[84:85], 0
	v_mov_b64_e32 v[86:87], 0
	v_mov_b64_e32 v[96:97], 0
	v_mov_b64_e32 v[98:99], 0
	v_mov_b64_e32 v[100:101], 0
	v_mov_b64_e32 v[102:103], 0
	v_mov_b64_e32 v[112:113], 0
	v_mov_b64_e32 v[114:115], 0
	v_mov_b64_e32 v[116:117], 0
	v_mov_b64_e32 v[118:119], 0
	v_mov_b64_e32 v[72:73], 0
	v_mov_b64_e32 v[74:75], 0
	v_mov_b64_e32 v[76:77], 0
	v_mov_b64_e32 v[78:79], 0
	v_mov_b64_e32 v[88:89], 0
	v_mov_b64_e32 v[90:91], 0
	v_mov_b64_e32 v[92:93], 0
	v_mov_b64_e32 v[94:95], 0
	v_mov_b64_e32 v[104:105], 0
	v_mov_b64_e32 v[106:107], 0
	v_mov_b64_e32 v[108:109], 0
	v_mov_b64_e32 v[110:111], 0
	v_mov_b64_e32 v[120:121], 0
	v_mov_b64_e32 v[122:123], 0
	v_mov_b64_e32 v[124:125], 0
	v_mov_b64_e32 v[126:127], 0
	s_cmpk_eq_i32 s58, 0x10
	s_cselect_b32 s101, 1, 0
	s_cmpk_eq_i32 s60, 0x100
	s_cselect_b32 s100, 2, 0
	s_or_b32 s101, s101, s100
	v_readfirstlane_b32 s100, v230
	s_lshr_b32 s100, s100, 5
	s_and_b32 s100, s100, 4
	s_bitcmp1_b32 s101, 0
	s_cselect_b32 s100, s100, 0
	s_or_b32 s101, s101, s100

;     __device__ __forceinline__ const char* a_of(const Unit& u) const { size_t o = A0; if constexpr (NG > 1 || UPT > 1) o = (u.g == 1) ? A1 : o; if constexpr (NG > 2) o = (u.g == 2) ? A2 : o; return (const char*)ws + o; }
;     __device__ __forceinline__ const char* b_of(const Unit& u) const { size_t o = B0; if constexpr (NG > 1 || UPT > 1) o = (u.g == 1) ? B1 : o; if constexpr (NG > 2) o = (u.g == 2) ? B2 : o; return (const char*)ws + o; }
; template <class Epi, class Sched>
; __device__ __forceinline__ void gemm_phase(LAS unsigned char* lds, const int K, const Sched& S, const Epi& E) {
;     ...
;         const bool has_next = S.next(ui + 1, nxt);
;         const char* nA = has_next ? S.a_of(nxt) + (size_t)nxt.pm * tstep : cA; const char* nB = has_next ? S.b_of(nxt) + (size_t)nxt.pn * tstep : cB;
;     ...
; #pragma unroll
;         for (int a = 0; a < 2; ++a)
; #pragma unroll
;             for (int b = 0; b < 2; ++b)
; #pragma unroll
;                 for (int m = 0; m < 4; ++m)
; #pragma unroll
;                     for (int n = 0; n < 2; ++n) acc[a][b][m][n] = (f32x4){0.f, 0.f, 0.f, 0.f};
.LBB0_735:
	s_ashr_i32 s39, s38, 31
	s_xor_b64 s[40:41], s[48:49], -1
	s_lshl_b64 s[42:43], s[38:39], 18
	s_cmp_eq_u32 s67, 1
	s_cselect_b32 s9, s3, 0x255d9000
	s_cselect_b32 s11, s4, 0x880000
	s_cmp_eq_u32 s67, 2
	s_cselect_b32 s9, 0xb80000, s9
	s_cselect_b32 s39, 0x29619000, s11
	s_add_u32 s9, s14, s9
	s_addc_u32 s11, s15, 0
	s_add_u32 s42, s9, s42
	s_addc_u32 s43, s11, s43
	s_and_b64 s[44:45], s[48:49], exec
	s_cselect_b32 s9, s43, s13
	s_cselect_b32 s11, s42, s12
	s_ashr_i32 s37, s36, 31
	s_lshl_b64 s[44:45], s[36:37], 18
	s_add_u32 s37, s14, s39
	s_addc_u32 s39, s15, 0
	s_add_u32 s44, s37, s44
	s_addc_u32 s45, s39, s45
	s_and_b64 s[48:49], s[48:49], exec
	s_cselect_b32 s37, s45, s47
	s_cselect_b32 s39, s44, s46
	s_add_u32 s12, s12, 0x20080
	s_addc_u32 s13, s13, 0
	s_add_u32 s71, s46, 0x100
	s_addc_u32 s72, s47, 0
	s_mov_b32 s73, -2
	v_mov_b64_e32 v[0:1], 0
	v_mov_b64_e32 v[2:3], 0
	v_mov_b64_e32 v[4:5], 0
	v_mov_b64_e32 v[6:7], 0
	v_mov_b64_e32 v[16:17], 0
	s_waitcnt vmcnt(0)
	v_mov_b64_e32 v[18:19], 0
	v_mov_b64_e32 v[20:21], 0
	v_mov_b64_e32 v[22:23], 0
	v_mov_b64_e32 v[32:33], 0
	v_mov_b64_e32 v[34:35], 0
	v_mov_b64_e32 v[36:37], 0
	v_mov_b64_e32 v[38:39], 0
	v_mov_b64_e32 v[48:49], 0
	v_mov_b64_e32 v[50:51], 0
	v_mov_b64_e32 v[52:53], 0
	v_mov_b64_e32 v[54:55], 0
	v_mov_b64_e32 v[8:9], 0
	v_mov_b64_e32 v[10:11], 0
	v_mov_b64_e32 v[12:13], 0
	v_mov_b64_e32 v[14:15], 0
	v_mov_b64_e32 v[24:25], 0
	v_mov_b64_e32 v[26:27], 0
	v_mov_b64_e32 v[28:29], 0
	v_mov_b64_e32 v[30:31], 0
	v_mov_b64_e32 v[40:41], 0
	v_mov_b64_e32 v[42:43], 0
	v_mov_b64_e32 v[44:45], 0
	v_mov_b64_e32 v[46:47], 0
	v_mov_b64_e32 v[56:57], 0
	v_mov_b64_e32 v[58:59], 0
	v_mov_b64_e32 v[60:61], 0
	v_mov_b64_e32 v[62:63], 0
	v_mov_b64_e32 v[64:65], 0
	v_mov_b64_e32 v[66:67], 0
	v_mov_b64_e32 v[68:69], 0
	v_mov_b64_e32 v[70:71], 0
	v_mov_b64_e32 v[80:81], 0
	v_mov_b64_e32 v[82:83], 0
	v_mov_b64_e32 v[84:85], 0
	v_mov_b64_e32 v[86:87], 0
	v_mov_b64_e32 v[100:101], 0
	v_mov_b64_e32 v[102:103], 0
	v_mov_b64_e32 v[104:105], 0
	v_mov_b64_e32 v[106:107], 0
	v_mov_b64_e32 v[136:137], 0
	v_mov_b64_e32 v[138:139], 0
	v_mov_b64_e32 v[140:141], 0
	v_mov_b64_e32 v[142:143], 0
	v_mov_b64_e32 v[72:73], 0
	v_mov_b64_e32 v[74:75], 0
	v_mov_b64_e32 v[76:77], 0
	v_mov_b64_e32 v[78:79], 0
	v_mov_b64_e32 v[88:89], 0
	v_mov_b64_e32 v[90:91], 0
	v_mov_b64_e32 v[92:93], 0
	v_mov_b64_e32 v[94:95], 0
	v_mov_b64_e32 v[128:129], 0
	v_mov_b64_e32 v[130:131], 0
	v_mov_b64_e32 v[132:133], 0
	v_mov_b64_e32 v[134:135], 0
	v_mov_b64_e32 v[152:153], 0
	v_mov_b64_e32 v[154:155], 0
	v_mov_b64_e32 v[156:157], 0
	v_mov_b64_e32 v[158:159], 0

; template <class Epi, class Sched>
; __device__ __forceinline__ void gemm_phase(LAS unsigned char* lds, const int K, const Sched& S, const Epi& E) {
;     ...
;         if (!E.keep_acc(cur))
; #pragma unroll
;         for (int a = 0; a < 2; ++a)
; #pragma unroll
;             for (int b = 0; b < 2; ++b)
; #pragma unroll
;                 for (int m = 0; m < 4; ++m)
; #pragma unroll
;                     for (int n = 0; n < 2; ++n) acc[a][b][m][n] = (f32x4){0.f, 0.f, 0.f, 0.f};
.LBB0_1191:
	s_and_b64 vcc, exec, s[8:9]
	s_cbranch_vccnz .LBB0_1098
	v_mov_b64_e32 v[0:1], 0
	v_mov_b64_e32 v[2:3], 0
	v_mov_b64_e32 v[4:5], 0
	v_mov_b64_e32 v[6:7], 0
	v_mov_b64_e32 v[8:9], 0
	v_mov_b64_e32 v[10:11], 0
	v_mov_b64_e32 v[12:13], 0
	v_mov_b64_e32 v[14:15], 0
	v_mov_b64_e32 v[16:17], 0
	v_mov_b64_e32 v[18:19], 0
	v_mov_b64_e32 v[20:21], 0
	v_mov_b64_e32 v[22:23], 0
	v_mov_b64_e32 v[24:25], 0
	v_mov_b64_e32 v[26:27], 0
	v_mov_b64_e32 v[28:29], 0
	v_mov_b64_e32 v[30:31], 0
	v_mov_b64_e32 v[32:33], 0
	v_mov_b64_e32 v[34:35], 0
	v_mov_b64_e32 v[36:37], 0
	v_mov_b64_e32 v[38:39], 0
	v_mov_b64_e32 v[40:41], 0
	v_mov_b64_e32 v[42:43], 0
	v_mov_b64_e32 v[44:45], 0
	v_mov_b64_e32 v[46:47], 0
	v_mov_b64_e32 v[48:49], 0
	v_mov_b64_e32 v[50:51], 0
	v_mov_b64_e32 v[52:53], 0
	v_mov_b64_e32 v[54:55], 0
	v_mov_b64_e32 v[56:57], 0
	v_mov_b64_e32 v[58:59], 0
	v_mov_b64_e32 v[60:61], 0
	v_mov_b64_e32 v[62:63], 0
	v_mov_b64_e32 v[64:65], 0
	v_mov_b64_e32 v[66:67], 0
	v_mov_b64_e32 v[68:69], 0
	v_mov_b64_e32 v[70:71], 0
	v_mov_b64_e32 v[72:73], 0
	v_mov_b64_e32 v[74:75], 0
	v_mov_b64_e32 v[76:77], 0
	v_mov_b64_e32 v[78:79], 0
	v_mov_b64_e32 v[80:81], 0
	v_mov_b64_e32 v[82:83], 0
	v_mov_b64_e32 v[84:85], 0
	v_mov_b64_e32 v[86:87], 0
	v_mov_b64_e32 v[88:89], 0
	v_mov_b64_e32 v[90:91], 0
	v_mov_b64_e32 v[92:93], 0
	v_mov_b64_e32 v[94:95], 0
	v_mov_b64_e32 v[96:97], 0
	v_mov_b64_e32 v[98:99], 0
	v_mov_b64_e32 v[100:101], 0
	v_mov_b64_e32 v[102:103], 0
	v_mov_b64_e32 v[104:105], 0
	v_mov_b64_e32 v[106:107], 0
	v_mov_b64_e32 v[108:109], 0
	v_mov_b64_e32 v[110:111], 0
	v_mov_b64_e32 v[112:113], 0
	v_mov_b64_e32 v[114:115], 0
	v_mov_b64_e32 v[116:117], 0
	v_mov_b64_e32 v[118:119], 0
	v_mov_b64_e32 v[120:121], 0
	v_mov_b64_e32 v[122:123], 0
	v_mov_b64_e32 v[124:125], 0
	v_mov_b64_e32 v[126:127], 0
	s_branch .LBB0_1098

;     __device__ __forceinline__ const char* a_of(const Unit& u) const { size_t o = A0; if constexpr (NG > 1 || UPT > 1) o = (u.g == 1) ? A1 : o; if constexpr (NG > 2) o = (u.g == 2) ? A2 : o; return (const char*)ws + o; }
;     __device__ __forceinline__ const char* b_of(const Unit& u) const { size_t o = B0; if constexpr (NG > 1 || UPT > 1) o = (u.g == 1) ? B1 : o; if constexpr (NG > 2) o = (u.g == 2) ? B2 : o; return (const char*)ws + o; }
; template <class Epi, class Sched>
; __device__ __forceinline__ void gemm_phase(LAS unsigned char* lds, const int K, const Sched& S, const Epi& E) {
;     ...
;         const bool has_next = S.next(ui + 1, nxt);
;         const char* nA = has_next ? S.a_of(nxt) + (size_t)nxt.pm * tstep : cA; const char* nB = has_next ? S.b_of(nxt) + (size_t)nxt.pn * tstep : cB;
;     ...
; #pragma unroll
;         for (int a = 0; a < 2; ++a)
; #pragma unroll
;             for (int b = 0; b < 2; ++b)
; #pragma unroll
;                 for (int m = 0; m < 4; ++m)
; #pragma unroll
;                     for (int n = 0; n < 2; ++n) acc[a][b][m][n] = (f32x4){0.f, 0.f, 0.f, 0.f};
.LBB0_1279:
	s_ashr_i32 s35, s34, 31
	s_lshl_b64 s[36:37], s[34:35], 19
	s_add_u32 s36, s33, s36
	s_addc_u32 s37, s42, s37
	s_and_b64 s[38:39], s[14:15], exec
	s_cselect_b32 s11, s37, s41
	s_cselect_b32 s13, s36, s40
	s_ashr_i32 s31, s30, 31
	s_lshl_b64 s[38:39], s[30:31], 19
	s_add_u32 s38, s3, s38
	s_addc_u32 s39, s4, s39
	s_and_b64 s[14:15], s[14:15], exec
	s_cselect_b32 s31, s39, s17
	s_cselect_b32 s35, s38, s16
	s_add_u32 s14, s40, 0x40080
	s_addc_u32 s15, s41, 0
	s_add_u32 s56, s16, 0x100
	s_addc_u32 s57, s17, 0
	s_mov_b32 s58, -2
	s_waitcnt lgkmcnt(0)
	v_mov_b64_e32 v[0:1], 0
	v_mov_b64_e32 v[2:3], 0
	v_mov_b64_e32 v[4:5], 0
	v_mov_b64_e32 v[6:7], 0
	v_mov_b64_e32 v[16:17], 0
	v_mov_b64_e32 v[18:19], 0
	v_mov_b64_e32 v[20:21], 0
	v_mov_b64_e32 v[22:23], 0
	v_mov_b64_e32 v[32:33], 0
	v_mov_b64_e32 v[34:35], 0
	v_mov_b64_e32 v[36:37], 0
	v_mov_b64_e32 v[38:39], 0
	v_mov_b64_e32 v[48:49], 0
	v_mov_b64_e32 v[50:51], 0
	v_mov_b64_e32 v[52:53], 0
	v_mov_b64_e32 v[54:55], 0
	v_mov_b64_e32 v[8:9], 0
	v_mov_b64_e32 v[10:11], 0
	v_mov_b64_e32 v[12:13], 0
	v_mov_b64_e32 v[14:15], 0
	v_mov_b64_e32 v[24:25], 0
	v_mov_b64_e32 v[26:27], 0
	v_mov_b64_e32 v[28:29], 0
	v_mov_b64_e32 v[30:31], 0
	v_mov_b64_e32 v[40:41], 0
	v_mov_b64_e32 v[42:43], 0
	v_mov_b64_e32 v[44:45], 0
	v_mov_b64_e32 v[46:47], 0
	v_mov_b64_e32 v[56:57], 0
	v_mov_b64_e32 v[58:59], 0
	v_mov_b64_e32 v[60:61], 0
	v_mov_b64_e32 v[62:63], 0
	v_mov_b64_e32 v[64:65], 0
	v_mov_b64_e32 v[66:67], 0
	v_mov_b64_e32 v[68:69], 0
	v_mov_b64_e32 v[70:71], 0
	v_mov_b64_e32 v[80:81], 0
	v_mov_b64_e32 v[82:83], 0
	v_mov_b64_e32 v[84:85], 0
	v_mov_b64_e32 v[86:87], 0
	v_mov_b64_e32 v[96:97], 0
	v_mov_b64_e32 v[98:99], 0
	v_mov_b64_e32 v[100:101], 0
	v_mov_b64_e32 v[102:103], 0
	v_mov_b64_e32 v[112:113], 0
	v_mov_b64_e32 v[114:115], 0
	v_mov_b64_e32 v[116:117], 0
	v_mov_b64_e32 v[118:119], 0
	v_mov_b64_e32 v[72:73], 0
	v_mov_b64_e32 v[74:75], 0
	v_mov_b64_e32 v[76:77], 0
	v_mov_b64_e32 v[78:79], 0
	v_mov_b64_e32 v[88:89], 0
	v_mov_b64_e32 v[90:91], 0
	v_mov_b64_e32 v[92:93], 0
	v_mov_b64_e32 v[94:95], 0
	v_mov_b64_e32 v[104:105], 0
	v_mov_b64_e32 v[106:107], 0
	v_mov_b64_e32 v[108:109], 0
	v_mov_b64_e32 v[110:111], 0
	v_mov_b64_e32 v[120:121], 0
	v_mov_b64_e32 v[122:123], 0
	v_mov_b64_e32 v[124:125], 0
	v_mov_b64_e32 v[126:127], 0
	s_cmpk_eq_i32 s12, 0x100
	s_cselect_b64 vcc, -1, 0

; template <class Epi, class Sched>
; __device__ __forceinline__ void gemm_phase(LAS unsigned char* lds, const int K, const Sched& S, const Epi& E) {
;     ...
; #pragma unroll
;         for (int a = 0; a < 2; ++a)
; #pragma unroll
;             for (int b = 0; b < 2; ++b)
; #pragma unroll
;                 for (int m = 0; m < 4; ++m)
; #pragma unroll
;                     for (int n = 0; n < 2; ++n) acc[a][b][m][n] = (f32x4){0.f, 0.f, 0.f, 0.f};
;     __device__ __forceinline__ void operator()(Acc& acc, const Unit& u, int wr, int wc, int fr, int fq) const {
;     ...
;             bf16_t* O = (bf16_t*)(ws + R_A); const float* ssq = (const float*)(ws + W_SSQ2);
;             float rsv[2][4];
; #pragma unroll
;             for (int ai = 0; ai < 2; ++ai)
; #pragma unroll
;                 for (int m = 0; m < 4; ++m) rsv[ai][m] = ssq[row0 + ai * 128 + m * 16];
.LBB0_1370:
	s_ashr_i32 s19, s18, 31
	s_lshl_b64 s[20:21], s[18:19], 19
	s_add_u32 s20, s33, s20
	s_addc_u32 s21, s34, s21
	s_and_b64 s[22:23], s[30:31], exec
	s_cselect_b32 s19, s21, s27
	s_cselect_b32 s44, s20, s26
	s_ashr_i32 s17, s16, 31
	s_lshl_b64 s[22:23], s[16:17], 19
	s_add_u32 s22, s3, s22
	s_addc_u32 s23, s4, s23
	s_and_b64 s[30:31], s[30:31], exec
	s_cselect_b32 s17, s23, s29
	s_cselect_b32 s45, s22, s28
	s_add_u32 s26, s26, 0x40080
	s_addc_u32 s27, s27, 0
	s_add_u32 s46, s28, 0x100
	s_addc_u32 s47, s29, 0
	s_mov_b32 s48, -2
	v_mov_b64_e32 v[0:1], 0
	v_mov_b64_e32 v[2:3], 0
	v_mov_b64_e32 v[4:5], 0
	v_mov_b64_e32 v[6:7], 0
	v_mov_b64_e32 v[16:17], 0
	v_mov_b64_e32 v[18:19], 0
	v_mov_b64_e32 v[20:21], 0
	v_mov_b64_e32 v[22:23], 0
	v_mov_b64_e32 v[32:33], 0
	v_mov_b64_e32 v[34:35], 0
	v_mov_b64_e32 v[36:37], 0
	v_mov_b64_e32 v[38:39], 0
	v_mov_b64_e32 v[48:49], 0
	v_mov_b64_e32 v[50:51], 0
	v_mov_b64_e32 v[52:53], 0
	v_mov_b64_e32 v[54:55], 0
	v_mov_b64_e32 v[8:9], 0
	v_mov_b64_e32 v[10:11], 0
	v_mov_b64_e32 v[12:13], 0
	v_mov_b64_e32 v[14:15], 0
	v_mov_b64_e32 v[24:25], 0
	v_mov_b64_e32 v[26:27], 0
	v_mov_b64_e32 v[28:29], 0
	v_mov_b64_e32 v[30:31], 0
	v_mov_b64_e32 v[40:41], 0
	v_mov_b64_e32 v[42:43], 0
	v_mov_b64_e32 v[44:45], 0
	v_mov_b64_e32 v[46:47], 0
	v_mov_b64_e32 v[56:57], 0
	v_mov_b64_e32 v[58:59], 0
	v_mov_b64_e32 v[60:61], 0
	v_mov_b64_e32 v[62:63], 0
	v_mov_b64_e32 v[64:65], 0
	v_mov_b64_e32 v[66:67], 0
	v_mov_b64_e32 v[72:73], 0
	v_mov_b64_e32 v[74:75], 0
	v_mov_b64_e32 v[80:81], 0
	v_mov_b64_e32 v[82:83], 0
	v_mov_b64_e32 v[88:89], 0
	v_mov_b64_e32 v[90:91], 0
	v_mov_b64_e32 v[96:97], 0
	v_mov_b64_e32 v[98:99], 0
	v_mov_b64_e32 v[104:105], 0
	v_mov_b64_e32 v[106:107], 0
	v_mov_b64_e32 v[112:113], 0
	v_mov_b64_e32 v[114:115], 0
	v_mov_b64_e32 v[116:117], 0
	v_mov_b64_e32 v[118:119], 0
	v_mov_b64_e32 v[68:69], 0
	v_mov_b64_e32 v[70:71], 0
	v_mov_b64_e32 v[76:77], 0
	v_mov_b64_e32 v[78:79], 0
	v_mov_b64_e32 v[84:85], 0
	v_mov_b64_e32 v[86:87], 0
	v_mov_b64_e32 v[92:93], 0
	v_mov_b64_e32 v[94:95], 0
	v_mov_b64_e32 v[100:101], 0
	v_mov_b64_e32 v[102:103], 0
	v_mov_b64_e32 v[108:109], 0
	v_mov_b64_e32 v[110:111], 0
	v_mov_b64_e32 v[120:121], 0
	v_mov_b64_e32 v[122:123], 0
	v_mov_b64_e32 v[124:125], 0
	v_mov_b64_e32 v[126:127], 0
	v_lshl_add_u32 v240, s24, 8, v150
	v_ashrrev_i32_e32 v241, 31, v240
	v_lshl_add_u64 v[240:241], v[240:241], 2, s[10:11]
	global_load_dword v232, v[240:241], off
	global_load_dword v233, v[240:241], off offset:64
	global_load_dword v234, v[240:241], off offset:128
	global_load_dword v235, v[240:241], off offset:192
	global_load_dword v236, v[240:241], off offset:512
	global_load_dword v237, v[240:241], off offset:576
	global_load_dword v238, v[240:241], off offset:640
	global_load_dword v239, v[240:241], off offset:704
	s_cmpk_eq_i32 s24, 0x100
	s_cselect_b64 vcc, -1, 0

; template <class Epi, class Sched>
; __device__ __forceinline__ void gemm_phase(LAS unsigned char* lds, const int K, const Sched& S, const Epi& E) {
;     ...
; #pragma unroll
;         for (int a = 0; a < 2; ++a)
; #pragma unroll
;             for (int b = 0; b < 2; ++b)
; #pragma unroll
;                 for (int m = 0; m < 4; ++m)
; #pragma unroll
;                     for (int n = 0; n < 2; ++n) acc[a][b][m][n] = (f32x4){0.f, 0.f, 0.f, 0.f};
.LBB0_1446:
	s_add_u32 s48, s14, 0x100
	s_addc_u32 s49, s15, 0
	s_mov_b32 s50, -2
	v_mov_b64_e32 v[0:1], 0
	v_mov_b64_e32 v[2:3], 0
	v_mov_b64_e32 v[4:5], 0
	v_mov_b64_e32 v[6:7], 0
	v_mov_b64_e32 v[16:17], 0
	v_mov_b64_e32 v[18:19], 0
	v_mov_b64_e32 v[20:21], 0
	v_mov_b64_e32 v[22:23], 0
	v_mov_b64_e32 v[32:33], 0
	v_mov_b64_e32 v[34:35], 0
	v_mov_b64_e32 v[36:37], 0
	v_mov_b64_e32 v[38:39], 0
	v_mov_b64_e32 v[48:49], 0
	v_mov_b64_e32 v[50:51], 0
	v_mov_b64_e32 v[52:53], 0
	v_mov_b64_e32 v[54:55], 0
	v_mov_b64_e32 v[8:9], 0
	v_mov_b64_e32 v[10:11], 0
	v_mov_b64_e32 v[12:13], 0
	v_mov_b64_e32 v[14:15], 0
	v_mov_b64_e32 v[24:25], 0
	v_mov_b64_e32 v[26:27], 0
	v_mov_b64_e32 v[28:29], 0
	v_mov_b64_e32 v[30:31], 0
	v_mov_b64_e32 v[40:41], 0
	v_mov_b64_e32 v[42:43], 0
	v_mov_b64_e32 v[44:45], 0
	v_mov_b64_e32 v[46:47], 0
	v_mov_b64_e32 v[56:57], 0
	v_mov_b64_e32 v[58:59], 0
	v_mov_b64_e32 v[60:61], 0
	v_mov_b64_e32 v[62:63], 0
	s_waitcnt vmcnt(16)
	v_mov_b64_e32 v[64:65], 0
	v_mov_b64_e32 v[66:67], 0
	v_mov_b64_e32 v[68:69], 0
	v_mov_b64_e32 v[70:71], 0
	v_mov_b64_e32 v[80:81], 0
	v_mov_b64_e32 v[82:83], 0
	v_mov_b64_e32 v[84:85], 0
	v_mov_b64_e32 v[86:87], 0
	v_mov_b64_e32 v[96:97], 0
	v_mov_b64_e32 v[98:99], 0
	v_mov_b64_e32 v[100:101], 0
	v_mov_b64_e32 v[102:103], 0
	v_mov_b64_e32 v[112:113], 0
	v_mov_b64_e32 v[114:115], 0
	v_mov_b64_e32 v[116:117], 0
	v_mov_b64_e32 v[118:119], 0
	v_mov_b64_e32 v[72:73], 0
	v_mov_b64_e32 v[74:75], 0
	v_mov_b64_e32 v[76:77], 0
	v_mov_b64_e32 v[78:79], 0
	v_mov_b64_e32 v[88:89], 0
	v_mov_b64_e32 v[90:91], 0
	v_mov_b64_e32 v[92:93], 0
	v_mov_b64_e32 v[94:95], 0
	v_mov_b64_e32 v[104:105], 0
	v_mov_b64_e32 v[106:107], 0
	v_mov_b64_e32 v[108:109], 0
	v_mov_b64_e32 v[110:111], 0
	v_mov_b64_e32 v[120:121], 0
	v_mov_b64_e32 v[122:123], 0
	v_mov_b64_e32 v[124:125], 0
	v_mov_b64_e32 v[126:127], 0
	s_cmpk_eq_i32 s47, 0x100
	s_cselect_b64 vcc, -1, 0
